# prompt attention inner loop: next 16-query group's Q fragments prefetched (software pipelined), first group's load shares the sink wait; on top of v29
# speedup vs baseline: 1.0037x; 1.0013x over previous
.LBB0_1402:
	s_bfe_u32 s58, s57, 0x30004
	s_lshl_b32 s28, s58, 9
	s_add_i32 s38, s52, s28
	s_ashr_i32 s46, s57, 7
	s_ashr_i32 s39, s38, 31
	s_ashr_i32 s47, s46, 31
	s_lshl_b64 s[38:39], s[38:39], 1
	s_and_b32 s28, s57, 15
	s_lshl_b64 s[48:49], s[46:47], 11
	s_cmp_lg_u32 s28, 0
	s_cbranch_scc0 .LBB0_1408
	s_lshl_b32 s28, s28, 7
	s_or_b32 s28, s48, s28
	s_add_u32 s50, s28, 0xffffff80
	s_addc_u32 s51, s49, -1
	v_lshl_add_u64 v[2:3], s[50:51], 0, v[58:59]
	v_mov_b64_e32 v[30:31], s[26:27]
	v_mad_u64_u32 v[6:7], s[60:61], v2, s53, v[30:31]
	v_mad_i32_i24 v7, v3, s53, v7
	s_lshl_b32 s28, s58, 7
	v_lshl_add_u64 v[2:3], v[6:7], 0, s[28:29]
	v_mov_b32_e32 v83, v4
	v_lshl_add_u64 v[2:3], v[2:3], 0, v[82:83]
	v_lshl_add_u64 v[6:7], v[2:3], 0, s[30:31]
	v_add_co_u32_e32 v2, vcc, s54, v2
	s_nop 1
	v_addc_co_u32_e32 v3, vcc, 0, v3, vcc
	global_load_dwordx4 v[6:9], v[6:7], off offset:1024
	s_nop 0
	global_load_dwordx4 v[10:13], v[2:3], off
	v_lshl_add_u64 v[2:3], s[50:51], 0, v[60:61]
	v_mad_u64_u32 v[14:15], s[60:61], v2, s53, v[30:31]
	v_mad_i32_i24 v15, v3, s53, v15
	v_lshl_add_u64 v[2:3], v[14:15], 0, s[28:29]
	v_lshl_add_u64 v[2:3], v[2:3], 0, v[82:83]
	v_lshl_add_u64 v[14:15], v[2:3], 0, s[30:31]
	v_add_co_u32_e32 v2, vcc, s54, v2
	s_nop 1
	v_addc_co_u32_e32 v3, vcc, 0, v3, vcc
	global_load_dwordx4 v[14:17], v[14:15], off offset:1024
	s_nop 0
	global_load_dwordx4 v[18:21], v[2:3], off
	v_lshl_add_u64 v[2:3], s[50:51], 0, v[62:63]
	v_mad_u64_u32 v[22:23], s[60:61], v2, s53, v[30:31]
	v_mad_i32_i24 v23, v3, s53, v23
	v_lshl_add_u64 v[2:3], v[22:23], 0, s[28:29]
	v_lshl_add_u64 v[2:3], v[2:3], 0, v[82:83]
	v_lshl_add_u64 v[22:23], v[2:3], 0, s[30:31]
	v_add_co_u32_e32 v2, vcc, s54, v2
	s_nop 1
	v_addc_co_u32_e32 v3, vcc, 0, v3, vcc
	global_load_dwordx4 v[22:25], v[22:23], off offset:1024
	s_nop 0
	global_load_dwordx4 v[26:29], v[2:3], off
	v_lshl_add_u64 v[2:3], s[50:51], 0, v[64:65]
	v_mad_u64_u32 v[30:31], s[50:51], v2, s53, v[30:31]
	v_mad_i32_i24 v31, v3, s53, v31
	v_lshl_add_u64 v[2:3], v[30:31], 0, s[28:29]
	v_lshl_add_u64 v[2:3], v[2:3], 0, v[82:83]
	v_lshl_add_u64 v[34:35], v[2:3], 0, s[30:31]
	v_add_co_u32_e32 v2, vcc, 0x2000, v2
	s_nop 1
	v_addc_co_u32_e32 v3, vcc, 0, v3, vcc
	global_load_dwordx4 v[30:33], v[2:3], off
	s_nop 0
	global_load_dwordx4 v[34:37], v[34:35], off offset:1024
	s_waitcnt vmcnt(6)
	ds_write_b128 v92, v[10:13]
	ds_write_b128 v92, v[6:9] offset:36864
	s_waitcnt vmcnt(4)
	ds_write_b128 v93, v[18:21]
	ds_write_b128 v93, v[14:17] offset:36864
	s_waitcnt vmcnt(3)
	ds_write_b128 v94, v[22:25] offset:36864
	s_waitcnt vmcnt(2)
	ds_write_b128 v94, v[26:29]
	s_waitcnt vmcnt(1)
	ds_write_b128 v95, v[30:33]
	s_waitcnt vmcnt(0)
	ds_write_b128 v95, v[34:37] offset:36864
	s_and_saveexec_b64 s[50:51], s[0:1]
	v_add_u32_e32 v2, v55, v88
	ds_write_b128 v2, v[100:103] offset:36864
	s_or_b64 exec, exec, s[50:51]
	s_and_b32 s28, s56, 15
	s_lshl_b32 s59, s28, 7
	s_lshl_b32 s28, s58, 3
	s_add_i32 s50, s28, s41
	s_ashr_i32 s51, s50, 31
	s_lshl_b64 s[50:51], s[50:51], 2
	s_add_u32 s50, s44, s50
	s_addc_u32 s51, s45, s51
	s_waitcnt lgkmcnt(0)
	s_barrier
	global_load_dword v5, v4, s[50:51]
	v_and_b32_e32 v7, 64, v96
	v_xor_b32_e32 v6, 16, v96
	v_add_u32_e32 v7, 64, v7
	v_xor_b32_e32 v8, 32, v96
	v_cmp_lt_i32_e32 vcc, v6, v7
	s_add_u32 s50, s59, s48
	s_addc_u32 s51, 0, s49
	v_cndmask_b32_e32 v6, v96, v6, vcc
	v_cmp_lt_i32_e32 vcc, v8, v7
	v_mov_b64_e32 v[2:3], s[38:39]
	v_lshlrev_b32_e32 v83, 2, v6
	v_cndmask_b32_e32 v7, v96, v8, vcc
	v_lshlrev_b32_e32 v98, 2, v7
	v_lshl_add_u64 v[6:7], s[50:51], 0, v[56:57]
	v_mad_u64_u32 v[2:3], s[50:51], v6, s53, v[2:3]
	v_lshlrev_b64 v[8:9], 13, v[6:7]
	v_mad_i32_i24 v3, v7, s53, v3
	v_lshl_add_u64 v[6:7], v[8:9], 0, s[38:39]
	s_mov_b32 s28, 0
	v_lshl_add_u64 v[84:85], v[74:75], 0, v[2:3]
	v_lshl_add_u64 v[86:87], v[76:77], 0, v[6:7]
	global_load_dwordx4 v[180:183], v[84:85], off offset:-64
	global_load_dwordx4 v[184:187], v[84:85], off
	v_lshl_add_u64 v[84:85], v[84:85], 0, s[34:35]
	s_waitcnt vmcnt(0)
	v_mul_f32_e32 v99, 0x3fb8aa3b, v5
	s_branch .Lattq_entry_A
.LBB0_1406:
	s_waitcnt vmcnt(4)
.Lattq_entry_A:
	v_mov_b64_e32 v[6:7], v[180:181]
	v_mov_b64_e32 v[8:9], v[182:183]
	v_mov_b64_e32 v[30:31], v[184:185]
	v_mov_b64_e32 v[32:33], v[186:187]
	global_load_dwordx4 v[180:183], v[84:85], off offset:-64
	global_load_dwordx4 v[184:187], v[84:85], off
	v_add_u32_e32 v2, s28, v90
	ds_read_b128 v[10:13], v2
	ds_read_b128 v[14:17], v2 offset:64
	ds_read_b128 v[18:21], v2 offset:2304
	ds_read_b128 v[22:25], v2 offset:2368
	ds_read_b128 v[26:29], v2 offset:4608
	ds_read_b128 v[104:107], v2 offset:4672
	v_mov_b32_e32 v5, v4
	v_lshl_add_u64 v[84:85], v[84:85], 0, s[34:35]
	s_waitcnt lgkmcnt(1)
	v_mfma_f32_16x16x32_bf16 v[108:111], v[26:29], v[6:9], 0
	ds_read_b128 v[26:29], v2 offset:6912
	ds_read_b128 v[112:115], v2 offset:6976
	s_waitcnt lgkmcnt(1)
	v_mfma_f32_16x16x32_bf16 v[116:119], v[26:29], v[6:9], 0
	ds_read_b128 v[26:29], v2 offset:9216
	ds_read_b128 v[120:123], v2 offset:9280
	s_waitcnt lgkmcnt(1)
	v_mfma_f32_16x16x32_bf16 v[124:127], v[26:29], v[6:9], 0
	ds_read_b128 v[26:29], v2 offset:11520
	ds_read_b128 v[128:131], v2 offset:11584
	s_waitcnt lgkmcnt(1)
	v_mfma_f32_16x16x32_bf16 v[132:135], v[26:29], v[6:9], 0
	ds_read_b128 v[26:29], v2 offset:13824
	ds_read_b128 v[136:139], v2 offset:13888
	s_waitcnt lgkmcnt(1)
	v_mfma_f32_16x16x32_bf16 v[140:143], v[26:29], v[6:9], 0
	ds_read_b128 v[26:29], v2 offset:16128
	ds_read_b128 v[46:49], v2 offset:16192
	v_mfma_f32_16x16x32_bf16 v[10:13], v[10:13], v[6:9], 0
	v_mfma_f32_16x16x32_bf16 v[18:21], v[18:21], v[6:9], 0
	s_waitcnt lgkmcnt(1)
	v_mfma_f32_16x16x32_bf16 v[50:53], v[26:29], v[6:9], 0
	ds_read_b128 v[26:29], v2 offset:18432
	ds_read_b128 v[38:41], v2 offset:18496
	v_mfma_f32_16x16x32_bf16 v[34:37], v[14:17], v[30:33], v[10:13]
	s_waitcnt lgkmcnt(1)
	v_mfma_f32_16x16x32_bf16 v[42:45], v[26:29], v[6:9], 0
	v_mfma_f32_16x16x32_bf16 v[26:29], v[22:25], v[30:33], v[18:21]
	s_nop 4
	v_mul_f32_e32 v2, 0x3e38aa3b, v34
	v_mul_f32_e32 v3, 0x3e38aa3b, v35
	v_mul_f32_e32 v34, 0x3e38aa3b, v36
	v_mfma_f32_16x16x32_bf16 v[22:25], v[104:107], v[30:33], v[108:111]
	v_mul_f32_e32 v35, 0x3e38aa3b, v37
	v_cndmask_b32_e64 v2, v97, v2, s[2:3]
	v_cndmask_b32_e64 v3, v97, v3, s[4:5]
	v_mfma_f32_16x16x32_bf16 v[18:21], v[112:115], v[30:33], v[116:119]
	v_cndmask_b32_e64 v34, v97, v34, s[6:7]
	v_cndmask_b32_e64 v35, v97, v35, s[8:9]
	v_mul_f32_e32 v36, 0x3e38aa3b, v26
	v_max3_f32 v118, v99, v2, v3
	v_mul_f32_e32 v37, 0x3e38aa3b, v27
	v_max3_f32 v118, v118, v34, v35
	v_mfma_f32_16x16x32_bf16 v[14:17], v[120:123], v[30:33], v[124:127]
	v_max3_f32 v36, v118, v36, v37
	v_add_u32_e32 v120, s28, v89
	s_addk_i32 s28, 0x900
	v_mfma_f32_16x16x32_bf16 v[10:13], v[128:131], v[30:33], v[132:135]
	s_cmpk_lg_i32 s28, 0x4800
	s_nop 2
	v_mul_f32_e32 v104, 0x3e38aa3b, v16
	v_mul_f32_e32 v105, 0x3e38aa3b, v17
	v_mfma_f32_16x16x32_bf16 v[6:9], v[136:139], v[30:33], v[140:143]
	v_mfma_f32_16x16x32_bf16 v[46:49], v[46:49], v[30:33], v[50:53]
	v_mul_f32_e32 v106, 0x3e38aa3b, v10
	v_mul_f32_e32 v107, 0x3e38aa3b, v11
	v_mul_f32_e32 v108, 0x3e38aa3b, v12
	s_waitcnt lgkmcnt(0)
	v_mfma_f32_16x16x32_bf16 v[30:33], v[38:41], v[30:33], v[42:45]
	v_mul_f32_e32 v38, 0x3e38aa3b, v28
	v_mul_f32_e32 v39, 0x3e38aa3b, v29
	v_mul_f32_e32 v40, 0x3e38aa3b, v22
	v_mul_f32_e32 v41, 0x3e38aa3b, v23
	v_max3_f32 v36, v36, v38, v39
	v_mul_f32_e32 v42, 0x3e38aa3b, v24
	v_mul_f32_e32 v43, 0x3e38aa3b, v25
	v_max3_f32 v36, v36, v40, v41
	v_mul_f32_e32 v44, 0x3e38aa3b, v18
	v_mul_f32_e32 v45, 0x3e38aa3b, v19
	v_max3_f32 v36, v36, v42, v43
	v_mul_f32_e32 v50, 0x3e38aa3b, v20
	v_mul_f32_e32 v51, 0x3e38aa3b, v21
	v_max3_f32 v36, v36, v44, v45
	v_mul_f32_e32 v52, 0x3e38aa3b, v14
	v_mul_f32_e32 v53, 0x3e38aa3b, v15
	v_max3_f32 v36, v36, v50, v51
	v_max3_f32 v36, v36, v52, v53
	v_max3_f32 v36, v36, v104, v105
	v_mul_f32_e32 v109, 0x3e38aa3b, v13
	v_max3_f32 v36, v36, v106, v107
	v_mul_f32_e32 v110, 0x3e38aa3b, v6
	v_mul_f32_e32 v111, 0x3e38aa3b, v7
	v_max3_f32 v36, v36, v108, v109
	v_mul_f32_e32 v112, 0x3e38aa3b, v8
	v_mul_f32_e32 v113, 0x3e38aa3b, v9
	v_max3_f32 v36, v36, v110, v111
	v_mul_f32_e32 v114, 0x3e38aa3b, v46
	v_mul_f32_e32 v115, 0x3e38aa3b, v47
	v_max3_f32 v36, v36, v112, v113
	v_mul_f32_e32 v116, 0x3e38aa3b, v48
	v_mul_f32_e32 v117, 0x3e38aa3b, v49
	v_mul_f32_e32 v30, 0x3e38aa3b, v30
	v_mul_f32_e32 v31, 0x3e38aa3b, v31
	v_max3_f32 v36, v36, v114, v115
	v_mul_f32_e32 v32, 0x3e38aa3b, v32
	v_mul_f32_e32 v33, 0x3e38aa3b, v33
	v_cndmask_b32_e64 v30, v97, v30, s[10:11]
	v_cndmask_b32_e64 v31, v97, v31, s[12:13]
	v_max3_f32 v36, v36, v116, v117
	v_cndmask_b32_e64 v32, v97, v32, s[14:15]
	v_cndmask_b32_e64 v33, v97, v33, s[16:17]
	v_max3_f32 v36, v36, v30, v31
	v_max3_f32 v36, v36, v32, v33
	ds_bpermute_b32 v37, v83, v36
	s_waitcnt lgkmcnt(0)
	v_max_f32_e32 v37, v37, v37
	v_max_f32_e32 v36, v36, v37
	ds_bpermute_b32 v37, v98, v36
	s_waitcnt lgkmcnt(0)
	v_max_f32_e32 v37, v37, v37
	v_max_f32_e32 v36, v36, v37
	v_sub_f32_e32 v2, v2, v36
	v_sub_f32_e32 v3, v3, v36
	v_sub_f32_e32 v34, v34, v36
	v_sub_f32_e32 v35, v35, v36
	v_fma_f32 v26, v26, s55, -v36
	v_fma_f32 v27, v27, s55, -v36
	v_fma_f32 v28, v28, s55, -v36
	v_fma_f32 v29, v29, s55, -v36
	v_fma_f32 v22, v22, s55, -v36
	v_fma_f32 v23, v23, s55, -v36
	v_fma_f32 v24, v24, s55, -v36
	v_fma_f32 v25, v25, s55, -v36
	v_fma_f32 v18, v18, s55, -v36
	v_fma_f32 v19, v19, s55, -v36
	v_fma_f32 v20, v20, s55, -v36
	v_fma_f32 v21, v21, s55, -v36
	v_fma_f32 v14, v14, s55, -v36
	v_fma_f32 v15, v15, s55, -v36
	v_fma_f32 v16, v16, s55, -v36
	v_fma_f32 v17, v17, s55, -v36
	v_fma_f32 v10, v10, s55, -v36
	v_fma_f32 v11, v11, s55, -v36
	v_fma_f32 v12, v12, s55, -v36
	v_fma_f32 v13, v13, s55, -v36
	v_fma_f32 v6, v6, s55, -v36
	v_fma_f32 v7, v7, s55, -v36
	v_fma_f32 v8, v8, s55, -v36
	v_fma_f32 v9, v9, s55, -v36
	v_exp_f32_e32 v2, v2
	v_exp_f32_e32 v121, v3
	v_exp_f32_e32 v122, v34
	v_exp_f32_e32 v123, v35
	v_exp_f32_e32 v124, v26
	v_exp_f32_e32 v125, v27
	v_exp_f32_e32 v126, v28
	v_exp_f32_e32 v127, v29
	v_exp_f32_e32 v128, v22
	v_exp_f32_e32 v129, v23
	v_exp_f32_e32 v130, v24
	v_exp_f32_e32 v131, v25
	v_exp_f32_e32 v132, v18
	v_exp_f32_e32 v133, v19
	v_exp_f32_e32 v134, v20
	v_exp_f32_e32 v135, v21
	v_exp_f32_e32 v136, v14
	v_exp_f32_e32 v137, v15
	v_exp_f32_e32 v138, v16
	v_exp_f32_e32 v139, v17
	v_exp_f32_e32 v140, v10
	v_exp_f32_e32 v141, v11
	v_exp_f32_e32 v142, v12
	v_exp_f32_e32 v143, v13
	v_exp_f32_e32 v144, v6
	v_exp_f32_e32 v145, v7
	v_exp_f32_e32 v146, v8
	v_exp_f32_e32 v147, v9
	v_cvt_pk_bf16_f32 v6, v2, v121
	v_cvt_pk_bf16_f32 v7, v122, v123
	v_cvt_pk_bf16_f32 v8, v124, v125
	v_cvt_pk_bf16_f32 v9, v126, v127
	ds_read_b64_tr_b16 v[10:11], v120 offset:36864
	ds_read_b64_tr_b16 v[14:15], v120 offset:36896
	ds_read_b64_tr_b16 v[18:19], v120 offset:36928
	ds_read_b64_tr_b16 v[22:23], v120 offset:36960
	ds_read_b64_tr_b16 v[12:13], v120 offset:39168
	ds_read_b64_tr_b16 v[16:17], v120 offset:39200
	ds_read_b64_tr_b16 v[20:21], v120 offset:39232
	ds_read_b64_tr_b16 v[24:25], v120 offset:39264
	v_fma_f32 v37, v46, s55, -v36
	v_fma_f32 v38, v47, s55, -v36
	v_fma_f32 v39, v48, s55, -v36
	v_fma_f32 v40, v49, s55, -v36
	v_sub_f32_e32 v30, v30, v36
	v_sub_f32_e32 v31, v31, v36
	v_sub_f32_e32 v32, v32, v36
	v_sub_f32_e32 v33, v33, v36
	v_sub_f32_e32 v36, v99, v36
	v_exp_f32_e32 v148, v37
	v_exp_f32_e32 v149, v38
	v_exp_f32_e32 v150, v39
	v_exp_f32_e32 v151, v40
	v_exp_f32_e32 v152, v30
	v_exp_f32_e32 v153, v31
	v_exp_f32_e32 v154, v32
	v_exp_f32_e32 v155, v33
	v_exp_f32_e32 v156, v36
	v_cvt_pk_bf16_f32 v26, v128, v129
	v_cvt_pk_bf16_f32 v27, v130, v131
	v_cvt_pk_bf16_f32 v28, v132, v133
	v_cvt_pk_bf16_f32 v29, v134, v135
	ds_read_b64_tr_b16 v[30:31], v120 offset:41472
	ds_read_b64_tr_b16 v[34:35], v120 offset:41504
	ds_read_b64_tr_b16 v[38:39], v120 offset:41536
	ds_read_b64_tr_b16 v[42:43], v120 offset:41568
	ds_read_b64_tr_b16 v[32:33], v120 offset:43776
	ds_read_b64_tr_b16 v[36:37], v120 offset:43808
	ds_read_b64_tr_b16 v[40:41], v120 offset:43840
	ds_read_b64_tr_b16 v[44:45], v120 offset:43872
	v_cvt_pk_bf16_f32 v46, v136, v137
	v_cvt_pk_bf16_f32 v47, v138, v139
	s_waitcnt lgkmcnt(11)
	v_mfma_f32_16x16x32_bf16 v[10:13], v[10:13], v[6:9], 0
	v_cvt_pk_bf16_f32 v48, v140, v141
	v_cvt_pk_bf16_f32 v49, v142, v143
	ds_read_b64_tr_b16 v[50:51], v120 offset:46080
	ds_read_b64_tr_b16 v[52:53], v120 offset:48384
	ds_read_b64_tr_b16 v[106:107], v120 offset:48416
	ds_read_b64_tr_b16 v[110:111], v120 offset:48448
	s_waitcnt lgkmcnt(13)
	v_mfma_f32_16x16x32_bf16 v[18:21], v[18:21], v[6:9], 0
	ds_read_b64_tr_b16 v[104:105], v120 offset:46112
	ds_read_b64_tr_b16 v[108:109], v120 offset:46144
	ds_read_b64_tr_b16 v[112:113], v120 offset:46176
	ds_read_b64_tr_b16 v[114:115], v120 offset:48480
	v_add_f32_e32 v157, 0, v2
	v_mfma_f32_16x16x32_bf16 v[14:17], v[14:17], v[6:9], 0
	s_waitcnt lgkmcnt(14)
	v_mfma_f32_16x16x32_bf16 v[6:9], v[22:25], v[6:9], 0
	v_cvt_pk_bf16_f32 v22, v144, v145
	v_cvt_pk_bf16_f32 v23, v146, v147
	v_cvt_pk_bf16_f32 v24, v148, v149
	s_waitcnt lgkmcnt(11)
	v_mfma_f32_16x16x32_bf16 v[10:13], v[30:33], v[26:29], v[10:13]
	v_cvt_pk_bf16_f32 v25, v150, v151
	ds_read_b64_tr_b16 v[30:31], v120 offset:50688
	s_waitcnt lgkmcnt(10)
	v_mfma_f32_16x16x32_bf16 v[18:21], v[38:41], v[26:29], v[18:21]
	v_mfma_f32_16x16x32_bf16 v[14:17], v[34:37], v[26:29], v[14:17]
	ds_read_b64_tr_b16 v[32:33], v120 offset:52992
	ds_read_b64_tr_b16 v[36:37], v120 offset:53024
	ds_read_b64_tr_b16 v[118:119], v120 offset:53056
	ds_read_b64_tr_b16 v[34:35], v120 offset:50720
	ds_read_b64_tr_b16 v[116:117], v120 offset:50752
	ds_read_b64_tr_b16 v[38:39], v120 offset:50784
	ds_read_b64_tr_b16 v[40:41], v120 offset:53088
	s_waitcnt lgkmcnt(14)
	v_mfma_f32_16x16x32_bf16 v[6:9], v[42:45], v[26:29], v[6:9]
	v_cvt_pk_bf16_f32 v2, v152, v153
	v_cvt_pk_bf16_f32 v3, v154, v155
	ds_read_b64_tr_b16 v[26:27], v120 offset:55296
	ds_read_b64_tr_b16 v[28:29], v120 offset:57600
	ds_read_b64_tr_b16 v[44:45], v120 offset:57632
	v_mfma_f32_16x16x32_bf16 v[10:13], v[50:53], v[46:49], v[10:13]
	s_waitcnt lgkmcnt(13)
	v_mfma_f32_16x16x32_bf16 v[18:21], v[108:111], v[46:49], v[18:21]
	v_add_f32_e32 v108, v121, v157
	v_mfma_f32_16x16x32_bf16 v[14:17], v[104:107], v[46:49], v[14:17]
	ds_read_b64_tr_b16 v[42:43], v120 offset:55328
	ds_read_b64_tr_b16 v[50:51], v120 offset:55360
	ds_read_b64_tr_b16 v[104:105], v120 offset:55392
	ds_read_b64_tr_b16 v[52:53], v120 offset:57664
	ds_read_b64_tr_b16 v[106:107], v120 offset:57696
	s_waitcnt lgkmcnt(14)
	v_mfma_f32_16x16x32_bf16 v[6:9], v[112:115], v[46:49], v[6:9]
	v_add_f32_e32 v46, v122, v108
	v_add_f32_e32 v46, v123, v46
	v_add_f32_e32 v46, v124, v46
	v_mfma_f32_16x16x32_bf16 v[10:13], v[30:33], v[22:25], v[10:13]
	v_add_f32_e32 v30, v125, v46
	v_add_f32_e32 v30, v126, v30
	v_add_f32_e32 v30, v127, v30
	v_add_f32_e32 v30, v128, v30
	v_add_f32_e32 v30, v129, v30
	v_add_f32_e32 v30, v130, v30
	v_add_f32_e32 v30, v131, v30
	v_add_f32_e32 v30, v132, v30
	v_add_f32_e32 v30, v133, v30
	s_waitcnt lgkmcnt(11)
	v_mfma_f32_16x16x32_bf16 v[14:17], v[34:37], v[22:25], v[14:17]
	s_waitcnt lgkmcnt(10)
	v_mfma_f32_16x16x32_bf16 v[18:21], v[116:119], v[22:25], v[18:21]
	s_waitcnt lgkmcnt(8)
	v_mfma_f32_16x16x32_bf16 v[6:9], v[38:41], v[22:25], v[6:9]
	v_add_f32_e32 v22, v134, v30
	v_add_f32_e32 v22, v135, v22
	v_add_f32_e32 v22, v136, v22
	v_add_f32_e32 v22, v137, v22
	v_add_f32_e32 v22, v138, v22
	v_add_f32_e32 v22, v139, v22
	v_add_f32_e32 v22, v140, v22
	v_add_f32_e32 v22, v141, v22
	v_add_f32_e32 v22, v142, v22
	v_add_f32_e32 v22, v143, v22
	v_add_f32_e32 v22, v144, v22
	v_add_f32_e32 v22, v145, v22
	s_waitcnt lgkmcnt(6)
	v_mfma_f32_16x16x32_bf16 v[10:13], v[26:29], v[2:5], v[10:13]
	s_waitcnt lgkmcnt(4)
	v_mfma_f32_16x16x32_bf16 v[14:17], v[42:45], v[2:5], v[14:17]
	s_waitcnt lgkmcnt(1)
	v_mfma_f32_16x16x32_bf16 v[18:21], v[50:53], v[2:5], v[18:21]
	s_waitcnt lgkmcnt(0)
	v_mfma_f32_16x16x32_bf16 v[6:9], v[104:107], v[2:5], v[6:9]
	v_add_f32_e32 v2, v146, v22
	v_add_f32_e32 v2, v147, v2
	v_add_f32_e32 v2, v148, v2
	v_add_f32_e32 v2, v149, v2
	v_add_f32_e32 v2, v150, v2
	v_add_f32_e32 v2, v151, v2
	v_add_f32_e32 v2, v152, v2
	v_add_f32_e32 v2, v153, v2
	v_add_f32_e32 v2, v154, v2
	v_add_f32_e32 v2, v155, v2
	ds_bpermute_b32 v3, v83, v2
	s_waitcnt lgkmcnt(0)
	v_add_f32_e32 v2, v2, v3
	ds_bpermute_b32 v3, v98, v2
	s_waitcnt lgkmcnt(0)
	v_add_f32_e32 v2, v2, v3
	v_add_f32_e32 v2, v156, v2
	v_div_scale_f32 v3, s[50:51], v2, v2, 1.0
	v_rcp_f32_e32 v22, v3
	v_div_scale_f32 v5, vcc, 1.0, v2, 1.0
	v_fma_f32 v23, -v3, v22, 1.0
	v_fmac_f32_e32 v22, v23, v22
	v_mul_f32_e32 v23, v5, v22
	v_fma_f32 v24, -v3, v23, v5
	v_fmac_f32_e32 v23, v24, v22
	v_fma_f32 v3, -v3, v23, v5
	v_div_fmas_f32 v3, v3, v22, v23
	v_div_fixup_f32 v2, v3, v2, 1.0
	v_mul_f32_e32 v3, v2, v10
	v_mul_f32_e32 v5, v2, v11
	v_mul_f32_e32 v10, v2, v12
	v_mul_f32_e32 v11, v2, v13
	v_mul_f32_e32 v12, v2, v14
	v_mul_f32_e32 v13, v2, v15
	v_mul_f32_e32 v14, v2, v16
	v_mul_f32_e32 v15, v2, v17
	v_mul_f32_e32 v16, v2, v18
	v_mul_f32_e32 v17, v2, v19
	v_mul_f32_e32 v18, v2, v20
	v_mul_f32_e32 v19, v2, v21
	v_mul_f32_e32 v6, v2, v6
	v_mul_f32_e32 v7, v2, v7
	v_mul_f32_e32 v8, v2, v8
	v_mul_f32_e32 v9, v2, v9
	v_cvt_pk_bf16_f32 v2, v3, v5
	v_cvt_pk_bf16_f32 v3, v10, v11
	global_store_dwordx2 v[86:87], v[2:3], off offset:-64
	v_cvt_pk_bf16_f32 v2, v12, v13
	v_cvt_pk_bf16_f32 v3, v14, v15
	global_store_dwordx2 v[86:87], v[2:3], off offset:-32
	v_cvt_pk_bf16_f32 v2, v16, v17
	v_cvt_pk_bf16_f32 v3, v18, v19
	global_store_dwordx2 v[86:87], v[2:3], off
	v_cvt_pk_bf16_f32 v2, v6, v7
	v_cvt_pk_bf16_f32 v3, v8, v9
	global_store_dwordx2 v[86:87], v[2:3], off offset:32
	v_lshl_add_u64 v[86:87], v[86:87], 0, s[36:37]
	s_cbranch_scc1 .LBB0_1406
	s_barrier
	s_branch .LBB0_1401

.LBB0_1417:
	s_or_b64 exec, exec, s[50:51]
	s_waitcnt vmcnt(1)
	ds_write_b128 v95, v[10:13]
	s_waitcnt vmcnt(0)
	ds_write_b128 v95, v[6:9] offset:36864
	s_and_saveexec_b64 s[48:49], s[0:1]
	v_add_u32_e32 v2, v55, v88
	ds_write_b128 v2, v[100:103] offset:36864
	s_or_b64 exec, exec, s[48:49]
	s_lshl_b32 s28, s58, 3
	s_add_i32 s48, s28, s41
	s_ashr_i32 s49, s48, 31
	s_lshl_b64 s[48:49], s[48:49], 2
	s_add_u32 s48, s44, s48
	s_addc_u32 s49, s45, s49
	s_waitcnt lgkmcnt(0)
	s_barrier
	global_load_dword v2, v4, s[48:49]
	v_and_b32_e32 v5, 64, v96
	s_mul_i32 s50, s46, 0x1400000
	v_xor_b32_e32 v3, 16, v96
	s_mul_hi_i32 s49, s46, 0x1400000
	v_add_u32_e32 v5, 64, v5
	s_add_u32 s50, s50, s38
	v_xor_b32_e32 v6, 32, v96
	v_cmp_lt_i32_e32 vcc, v3, v5
	s_addc_u32 s51, s49, s39
	s_lshl_b64 s[46:47], s[46:47], 24
	v_cndmask_b32_e32 v3, v96, v3, vcc
	v_cmp_lt_i32_e32 vcc, v6, v5
	s_add_u32 s38, s46, s38
	s_addc_u32 s39, s47, s39
	v_cndmask_b32_e32 v5, v96, v6, vcc
	s_mov_b32 s28, 0
	s_movk_i32 s48, 0xffc0
	v_lshlrev_b32_e32 v83, 2, v3
	v_lshlrev_b32_e32 v84, 2, v5
	v_lshl_add_u64 v[50:51], v[78:79], 0, s[50:51]
	v_lshl_add_u64 v[52:53], v[80:81], 0, s[38:39]
	s_mov_b32 s38, 0
	global_load_dwordx4 v[180:183], v[50:51], off offset:-64
	global_load_dwordx4 v[184:187], v[50:51], off
	v_lshl_add_u64 v[50:51], v[50:51], 0, s[34:35]
	s_waitcnt vmcnt(0)
	v_mul_f32_e32 v85, 0x3fb8aa3b, v2
	v_max_f32_e32 v86, 0xff800000, v85
	s_branch .Lattq_entry_B

.Lattq_entry_B:
	v_mov_b64_e32 v[10:11], v[180:181]
	v_mov_b64_e32 v[12:13], v[182:183]
	v_mov_b64_e32 v[6:7], v[184:185]
	v_mov_b64_e32 v[8:9], v[186:187]
	global_load_dwordx4 v[180:183], v[50:51], off offset:-64
	global_load_dwordx4 v[184:187], v[50:51], off
	v_add_u32_e32 v2, s28, v91
	ds_read_b128 v[14:17], v2
	ds_read_b128 v[18:21], v2 offset:64
	ds_read_b128 v[22:25], v2 offset:2304
	ds_read_b128 v[26:29], v2 offset:2368
	ds_read_b128 v[30:33], v2 offset:4608
	ds_read_b128 v[104:107], v2 offset:4672
	s_add_i32 s39, s38, 1
	s_cmp_gt_u32 s38, 6
	s_mov_b32 s38, s39
	s_cselect_b64 vcc, -1, 0
	s_sub_i32 s39, s48, 32
	s_cmp_lt_u32 s39, 0xffffff80
	v_add_u32_e32 v87, s28, v89
	v_mov_b32_e32 v5, v4
	v_lshl_add_u64 v[50:51], v[50:51], 0, s[34:35]
	s_waitcnt lgkmcnt(1)
	v_mfma_f32_16x16x32_bf16 v[108:111], v[30:33], v[10:13], 0
	ds_read_b128 v[30:33], v2 offset:6912
	ds_read_b128 v[112:115], v2 offset:6976
	s_waitcnt lgkmcnt(1)
	v_mfma_f32_16x16x32_bf16 v[116:119], v[30:33], v[10:13], 0
	ds_read_b128 v[30:33], v2 offset:9216
	ds_read_b128 v[120:123], v2 offset:9280
	s_waitcnt lgkmcnt(1)
	v_mfma_f32_16x16x32_bf16 v[124:127], v[30:33], v[10:13], 0
	ds_read_b128 v[30:33], v2 offset:11520
	ds_read_b128 v[128:131], v2 offset:11584
	s_waitcnt lgkmcnt(1)
	v_mfma_f32_16x16x32_bf16 v[132:135], v[30:33], v[10:13], 0
	ds_read_b128 v[30:33], v2 offset:13824
	ds_read_b128 v[42:45], v2 offset:13888
	v_mfma_f32_16x16x32_bf16 v[14:17], v[14:17], v[10:13], 0
	s_waitcnt lgkmcnt(1)
	v_mfma_f32_16x16x32_bf16 v[46:49], v[30:33], v[10:13], 0
	ds_read_b128 v[30:33], v2 offset:16128
	ds_read_b128 v[34:37], v2 offset:16192
	v_mfma_f32_16x16x32_bf16 v[22:25], v[22:25], v[10:13], 0
	s_waitcnt lgkmcnt(1)
	v_mfma_f32_16x16x32_bf16 v[38:41], v[30:33], v[10:13], 0
	v_mfma_f32_16x16x32_bf16 v[30:33], v[18:21], v[6:9], v[14:17]
	v_mfma_f32_16x16x32_bf16 v[26:29], v[26:29], v[6:9], v[22:25]
	v_mfma_f32_16x16x32_bf16 v[22:25], v[104:107], v[6:9], v[108:111]
	s_nop 5
	v_mul_f32_e32 v2, 0x3e38aa3b, v30
	v_mul_f32_e32 v3, 0x3e38aa3b, v31
	v_mul_f32_e32 v30, 0x3e38aa3b, v32
	v_mul_f32_e32 v31, 0x3e38aa3b, v33
	v_cndmask_b32_e32 v2, v97, v2, vcc
	v_cndmask_b32_e32 v3, v97, v3, vcc
	v_cndmask_b32_e32 v30, v97, v30, vcc
	v_cndmask_b32_e32 v31, v97, v31, vcc
	s_cselect_b64 vcc, -1, 0
	s_sub_i32 s39, s48, 31
	v_mul_f32_e32 v26, 0x3e38aa3b, v26
	s_cmp_lt_u32 s39, 0xffffff80
	v_cndmask_b32_e32 v26, v97, v26, vcc
	s_cselect_b64 vcc, -1, 0
	s_sub_i32 s39, s48, 30
	v_mul_f32_e32 v27, 0x3e38aa3b, v27
	s_cmp_lt_u32 s39, 0xffffff80
	v_cndmask_b32_e32 v27, v97, v27, vcc
	s_cselect_b64 vcc, -1, 0
	s_sub_i32 s39, s48, 29
	v_mul_f32_e32 v28, 0x3e38aa3b, v28
	s_cmp_lt_u32 s39, 0xffffff80
	v_cndmask_b32_e32 v28, v97, v28, vcc
	s_cselect_b64 vcc, -1, 0
	s_add_i32 s39, s48, -16
	v_mul_f32_e32 v29, 0x3e38aa3b, v29
	s_cmp_lt_u32 s39, 0xffffff80
	v_cndmask_b32_e32 v29, v97, v29, vcc
	s_cselect_b64 vcc, -1, 0
	s_add_i32 s39, s48, -15
	v_mul_f32_e32 v22, 0x3e38aa3b, v22
	s_cmp_lt_u32 s39, 0xffffff80
	v_cndmask_b32_e32 v22, v97, v22, vcc
	s_cselect_b64 vcc, -1, 0
	s_add_i32 s39, s48, -14
	v_mul_f32_e32 v23, 0x3e38aa3b, v23
	s_cmp_lt_u32 s39, 0xffffff80
	v_mfma_f32_16x16x32_bf16 v[18:21], v[112:115], v[6:9], v[116:119]
	v_cndmask_b32_e32 v23, v97, v23, vcc
	s_cselect_b64 vcc, -1, 0
	s_add_i32 s39, s48, -13
	v_mul_f32_e32 v24, 0x3e38aa3b, v24
	s_cmp_lt_u32 s39, 0xffffff80
	v_mul_f32_e32 v25, 0x3e38aa3b, v25
	v_cndmask_b32_e32 v24, v97, v24, vcc
	s_cselect_b64 vcc, -1, 0
	s_cmp_lt_u32 s48, 0xffffff80
	v_cndmask_b32_e32 v25, v97, v25, vcc
	s_cselect_b64 vcc, -1, 0
	s_add_i32 s39, s48, 1
	v_mul_f32_e32 v18, 0x3e38aa3b, v18
	s_cmp_lt_u32 s39, 0xffffff80
	v_cndmask_b32_e32 v18, v97, v18, vcc
	s_cselect_b64 vcc, -1, 0
	s_add_i32 s39, s48, 2
	v_mul_f32_e32 v19, 0x3e38aa3b, v19
	s_cmp_lt_u32 s39, 0xffffff80
	v_cndmask_b32_e32 v19, v97, v19, vcc
	s_cselect_b64 vcc, -1, 0
	s_add_i32 s39, s48, 3
	v_mfma_f32_16x16x32_bf16 v[14:17], v[120:123], v[6:9], v[124:127]
	v_mul_f32_e32 v20, 0x3e38aa3b, v20
	s_cmp_lt_u32 s39, 0xffffff80
	v_cndmask_b32_e32 v20, v97, v20, vcc
	s_cselect_b64 vcc, -1, 0
	s_add_i32 s39, s48, 16
	v_mul_f32_e32 v21, 0x3e38aa3b, v21
	s_cmp_lt_u32 s39, 0xffffff80
	v_cndmask_b32_e32 v21, v97, v21, vcc
	s_cselect_b64 vcc, -1, 0
	s_add_i32 s46, s48, 17
	v_mul_f32_e32 v14, 0x3e38aa3b, v14
	s_cmp_lt_u32 s46, 0xffffff80
	v_cndmask_b32_e32 v14, v97, v14, vcc
	s_cselect_b64 vcc, -1, 0
	s_add_i32 s46, s48, 18
	v_mul_f32_e32 v15, 0x3e38aa3b, v15
	s_cmp_lt_u32 s46, 0xffffff80
	v_cndmask_b32_e32 v15, v97, v15, vcc
	s_cselect_b64 vcc, -1, 0
	s_add_i32 s46, s48, 19
	v_mfma_f32_16x16x32_bf16 v[10:13], v[128:131], v[6:9], v[132:135]
	v_mul_f32_e32 v16, 0x3e38aa3b, v16
	s_cmp_lt_u32 s46, 0xffffff80
	v_cndmask_b32_e32 v16, v97, v16, vcc
	s_cselect_b64 vcc, -1, 0
	s_add_i32 s46, s48, 32
	v_mul_f32_e32 v17, 0x3e38aa3b, v17
	s_cmp_lt_u32 s46, 0xffffff80
	v_cndmask_b32_e32 v17, v97, v17, vcc
	s_cselect_b64 vcc, -1, 0
	s_add_i32 s46, s48, 33
	v_mul_f32_e32 v10, 0x3e38aa3b, v10
	s_cmp_lt_u32 s46, 0xffffff80
	v_cndmask_b32_e32 v10, v97, v10, vcc
	s_cselect_b64 vcc, -1, 0
	s_add_i32 s46, s48, 34
	v_mfma_f32_16x16x32_bf16 v[42:45], v[42:45], v[6:9], v[46:49]
	v_mul_f32_e32 v11, 0x3e38aa3b, v11
	s_cmp_lt_u32 s46, 0xffffff80
	v_cndmask_b32_e32 v11, v97, v11, vcc
	s_waitcnt lgkmcnt(0)
	v_mfma_f32_16x16x32_bf16 v[6:9], v[34:37], v[6:9], v[38:41]
	v_max3_f32 v36, v86, v2, v3
	v_max3_f32 v36, v36, v30, v31
	s_cselect_b64 vcc, -1, 0
	s_add_i32 s46, s48, 35
	v_mul_f32_e32 v12, 0x3e38aa3b, v12
	v_max3_f32 v36, v36, v26, v27
	s_cmp_lt_u32 s46, 0xffffff80
	v_max3_f32 v36, v36, v28, v29
	v_cndmask_b32_e32 v12, v97, v12, vcc
	s_cselect_b64 vcc, -1, 0
	s_add_i32 s46, s48, 48
	v_mul_f32_e32 v13, 0x3e38aa3b, v13
	v_max3_f32 v36, v36, v22, v23
	s_cmp_lt_u32 s46, 0xffffff80
	v_max3_f32 v36, v36, v24, v25
	v_cndmask_b32_e32 v13, v97, v13, vcc
	s_cselect_b64 vcc, -1, 0
	s_add_i32 s46, s48, 49
	v_mul_f32_e32 v32, 0x3e38aa3b, v42
	v_max3_f32 v36, v36, v18, v19
	s_cmp_lt_u32 s46, 0xffffff80
	v_max3_f32 v36, v36, v20, v21
	v_cndmask_b32_e32 v32, v97, v32, vcc
	s_cselect_b64 vcc, -1, 0
	s_add_i32 s46, s48, 50
	v_mul_f32_e32 v33, 0x3e38aa3b, v43
	v_max3_f32 v36, v36, v14, v15
	s_cmp_lt_u32 s46, 0xffffff80
	v_max3_f32 v36, v36, v16, v17
	v_cndmask_b32_e32 v33, v97, v33, vcc
	s_cselect_b64 vcc, -1, 0
	s_add_i32 s46, s48, 51
	v_mul_f32_e32 v34, 0x3e38aa3b, v44
	v_max3_f32 v36, v36, v10, v11
	s_cmp_lt_u32 s46, 0xffffff80
	v_mul_f32_e32 v35, 0x3e38aa3b, v45
	v_max3_f32 v36, v36, v12, v13
	v_cndmask_b32_e32 v34, v97, v34, vcc
	s_cselect_b64 vcc, -1, 0
	v_mul_f32_e32 v6, 0x3e38aa3b, v6
	v_mul_f32_e32 v7, 0x3e38aa3b, v7
	v_max3_f32 v36, v36, v32, v33
	v_cndmask_b32_e32 v35, v97, v35, vcc
	v_mul_f32_e32 v8, 0x3e38aa3b, v8
	v_mul_f32_e32 v9, 0x3e38aa3b, v9
	v_cndmask_b32_e64 v6, v97, v6, s[10:11]
	v_cndmask_b32_e64 v7, v97, v7, s[12:13]
	v_max3_f32 v36, v36, v34, v35
	v_cndmask_b32_e64 v8, v97, v8, s[14:15]
	v_cndmask_b32_e64 v9, v97, v9, s[16:17]
	v_max3_f32 v36, v36, v6, v7
	v_max3_f32 v36, v36, v8, v9
	ds_bpermute_b32 v37, v83, v36
	s_addk_i32 s28, 0x900
	s_mov_b32 s48, s39
	s_cmpk_lg_i32 s28, 0x4800
	s_waitcnt lgkmcnt(0)
	v_max_f32_e32 v37, v37, v37
	v_max_f32_e32 v36, v36, v37
	ds_bpermute_b32 v37, v84, v36
	s_waitcnt lgkmcnt(0)
	v_max_f32_e32 v37, v37, v37
	v_max_f32_e32 v36, v36, v37
	v_sub_f32_e32 v37, 0xff800000, v36
	v_sub_f32_e32 v2, v2, v36
	v_sub_f32_e32 v3, v3, v36
	v_sub_f32_e32 v30, v30, v36
	v_sub_f32_e32 v31, v31, v36
	v_sub_f32_e32 v22, v22, v36
	v_sub_f32_e32 v23, v23, v36
	v_sub_f32_e32 v24, v24, v36
	v_sub_f32_e32 v25, v25, v36
	v_sub_f32_e32 v18, v18, v36
	v_sub_f32_e32 v19, v19, v36
	v_sub_f32_e32 v20, v20, v36
	v_sub_f32_e32 v21, v21, v36
	v_sub_f32_e32 v14, v14, v36
	v_sub_f32_e32 v15, v15, v36
	v_sub_f32_e32 v16, v16, v36
	v_sub_f32_e32 v17, v17, v36
	v_sub_f32_e32 v10, v10, v36
	v_sub_f32_e32 v11, v11, v36
	v_sub_f32_e32 v12, v12, v36
	v_sub_f32_e32 v13, v13, v36
	v_sub_f32_e32 v6, v6, v36
	v_sub_f32_e32 v7, v7, v36
	v_sub_f32_e32 v8, v8, v36
	v_sub_f32_e32 v9, v9, v36
	v_exp_f32_e32 v98, v37
	v_exp_f32_e32 v99, v2
	v_exp_f32_e32 v124, v3
	v_exp_f32_e32 v125, v30
	v_exp_f32_e32 v126, v31
	v_exp_f32_e32 v131, v22
	v_exp_f32_e32 v132, v23
	v_exp_f32_e32 v133, v24
	v_exp_f32_e32 v134, v25
	v_exp_f32_e32 v135, v18
	v_exp_f32_e32 v136, v19
	v_exp_f32_e32 v137, v20
	v_exp_f32_e32 v138, v21
	v_exp_f32_e32 v139, v14
	v_exp_f32_e32 v140, v15
	v_exp_f32_e32 v141, v16
	v_exp_f32_e32 v142, v17
	v_exp_f32_e32 v143, v10
	v_exp_f32_e32 v144, v11
	v_exp_f32_e32 v145, v12
	v_exp_f32_e32 v146, v13
	v_exp_f32_e32 v151, v6
	v_exp_f32_e32 v152, v7
	v_exp_f32_e32 v153, v8
	v_exp_f32_e32 v154, v9
	v_cvt_pk_bf16_f32 v6, v98, v98
	v_cvt_pk_bf16_f32 v7, v98, v98
	v_cvt_pk_bf16_f32 v8, v99, v124
	v_cvt_pk_bf16_f32 v9, v125, v126
	ds_read_b64_tr_b16 v[10:11], v87 offset:36864
	ds_read_b64_tr_b16 v[14:15], v87 offset:36896
	ds_read_b64_tr_b16 v[18:19], v87 offset:36928
	ds_read_b64_tr_b16 v[22:23], v87 offset:36960
	ds_read_b64_tr_b16 v[12:13], v87 offset:39168
	ds_read_b64_tr_b16 v[16:17], v87 offset:39200
	ds_read_b64_tr_b16 v[20:21], v87 offset:39232
	ds_read_b64_tr_b16 v[24:25], v87 offset:39264
	v_sub_f32_e32 v26, v26, v36
	v_sub_f32_e32 v27, v27, v36
	v_sub_f32_e32 v28, v28, v36
	v_sub_f32_e32 v29, v29, v36
	v_sub_f32_e32 v32, v32, v36
	v_sub_f32_e32 v33, v33, v36
	v_sub_f32_e32 v34, v34, v36
	v_sub_f32_e32 v35, v35, v36
	v_sub_f32_e32 v36, v85, v36
	v_exp_f32_e32 v127, v26
	v_exp_f32_e32 v128, v27
	v_exp_f32_e32 v129, v28
	v_exp_f32_e32 v130, v29
	v_exp_f32_e32 v147, v32
	v_exp_f32_e32 v148, v33
	v_exp_f32_e32 v149, v34
	v_exp_f32_e32 v150, v35
	v_exp_f32_e32 v155, v36
	v_cvt_pk_bf16_f32 v26, v127, v128
	v_cvt_pk_bf16_f32 v27, v129, v130
	v_cvt_pk_bf16_f32 v28, v131, v132
	v_cvt_pk_bf16_f32 v29, v133, v134
	ds_read_b64_tr_b16 v[30:31], v87 offset:41472
	ds_read_b64_tr_b16 v[34:35], v87 offset:41504
	ds_read_b64_tr_b16 v[38:39], v87 offset:41536
	ds_read_b64_tr_b16 v[42:43], v87 offset:41568
	ds_read_b64_tr_b16 v[32:33], v87 offset:43776
	ds_read_b64_tr_b16 v[36:37], v87 offset:43808
	ds_read_b64_tr_b16 v[40:41], v87 offset:43840
	ds_read_b64_tr_b16 v[44:45], v87 offset:43872
	v_cvt_pk_bf16_f32 v46, v135, v136
	v_cvt_pk_bf16_f32 v47, v137, v138
	s_waitcnt lgkmcnt(11)
	v_mfma_f32_16x16x32_bf16 v[10:13], v[10:13], v[6:9], 0
	v_cvt_pk_bf16_f32 v48, v139, v140
	v_cvt_pk_bf16_f32 v49, v141, v142
	ds_read_b64_tr_b16 v[104:105], v87 offset:46080
	s_waitcnt lgkmcnt(11)
	v_mfma_f32_16x16x32_bf16 v[14:17], v[14:17], v[6:9], 0
	ds_read_b64_tr_b16 v[106:107], v87 offset:48384
	ds_read_b64_tr_b16 v[110:111], v87 offset:48416
	ds_read_b64_tr_b16 v[114:115], v87 offset:48448
	ds_read_b64_tr_b16 v[108:109], v87 offset:46112
	ds_read_b64_tr_b16 v[112:113], v87 offset:46144
	ds_read_b64_tr_b16 v[116:117], v87 offset:46176
	ds_read_b64_tr_b16 v[118:119], v87 offset:48480
	s_waitcnt lgkmcnt(14)
	v_mfma_f32_16x16x32_bf16 v[18:21], v[18:21], v[6:9], 0
	v_add_f32_e32 v156, 0, v98
	v_mfma_f32_16x16x32_bf16 v[6:9], v[22:25], v[6:9], 0
	v_cvt_pk_bf16_f32 v22, v143, v144
	v_cvt_pk_bf16_f32 v23, v145, v146
	v_cvt_pk_bf16_f32 v24, v147, v148
	s_waitcnt lgkmcnt(11)
	v_mfma_f32_16x16x32_bf16 v[10:13], v[30:33], v[26:29], v[10:13]
	v_cvt_pk_bf16_f32 v25, v149, v150
	ds_read_b64_tr_b16 v[30:31], v87 offset:50688
	s_waitcnt lgkmcnt(11)
	v_mfma_f32_16x16x32_bf16 v[14:17], v[34:37], v[26:29], v[14:17]
	ds_read_b64_tr_b16 v[32:33], v87 offset:52992
	ds_read_b64_tr_b16 v[36:37], v87 offset:53024
	ds_read_b64_tr_b16 v[122:123], v87 offset:53056
	s_waitcnt lgkmcnt(13)
	v_mfma_f32_16x16x32_bf16 v[18:21], v[38:41], v[26:29], v[18:21]
	ds_read_b64_tr_b16 v[34:35], v87 offset:50720
	ds_read_b64_tr_b16 v[120:121], v87 offset:50752
	ds_read_b64_tr_b16 v[38:39], v87 offset:50784
	ds_read_b64_tr_b16 v[40:41], v87 offset:53088
	v_cvt_pk_bf16_f32 v2, v151, v152
	s_waitcnt lgkmcnt(14)
	v_mfma_f32_16x16x32_bf16 v[6:9], v[42:45], v[26:29], v[6:9]
	v_cvt_pk_bf16_f32 v3, v153, v154
	ds_read_b64_tr_b16 v[26:27], v87 offset:55296
	ds_read_b64_tr_b16 v[28:29], v87 offset:57600
	ds_read_b64_tr_b16 v[44:45], v87 offset:57632
	v_mfma_f32_16x16x32_bf16 v[10:13], v[104:107], v[46:49], v[10:13]
	s_waitcnt lgkmcnt(14)
	v_mfma_f32_16x16x32_bf16 v[14:17], v[108:111], v[46:49], v[14:17]
	ds_read_b64_tr_b16 v[42:43], v87 offset:55328
	ds_read_b64_tr_b16 v[104:105], v87 offset:55360
	ds_read_b64_tr_b16 v[108:109], v87 offset:55392
	ds_read_b64_tr_b16 v[106:107], v87 offset:57664
	ds_read_b64_tr_b16 v[110:111], v87 offset:57696
	v_add_f32_e32 v87, v98, v156
	s_waitcnt lgkmcnt(14)
	v_mfma_f32_16x16x32_bf16 v[18:21], v[112:115], v[46:49], v[18:21]
	v_mfma_f32_16x16x32_bf16 v[6:9], v[116:119], v[46:49], v[6:9]
	v_add_f32_e32 v46, v98, v87
	v_add_f32_e32 v46, v98, v46
	v_add_f32_e32 v46, v99, v46
	v_mfma_f32_16x16x32_bf16 v[10:13], v[30:33], v[22:25], v[10:13]
	v_add_f32_e32 v30, v124, v46
	v_add_f32_e32 v30, v125, v30
	v_add_f32_e32 v30, v126, v30
	v_add_f32_e32 v30, v127, v30
	v_add_f32_e32 v30, v128, v30
	v_add_f32_e32 v30, v129, v30
	v_add_f32_e32 v30, v130, v30
	v_add_f32_e32 v30, v131, v30
	v_add_f32_e32 v30, v132, v30
	s_waitcnt lgkmcnt(11)
	v_mfma_f32_16x16x32_bf16 v[14:17], v[34:37], v[22:25], v[14:17]
	s_waitcnt lgkmcnt(10)
	v_mfma_f32_16x16x32_bf16 v[18:21], v[120:123], v[22:25], v[18:21]
	s_waitcnt lgkmcnt(8)
	v_mfma_f32_16x16x32_bf16 v[6:9], v[38:41], v[22:25], v[6:9]
	v_add_f32_e32 v22, v133, v30
	v_add_f32_e32 v22, v134, v22
	v_add_f32_e32 v22, v135, v22
	v_add_f32_e32 v22, v136, v22
	v_add_f32_e32 v22, v137, v22
	v_add_f32_e32 v22, v138, v22
	v_add_f32_e32 v22, v139, v22
	v_add_f32_e32 v22, v140, v22
	v_add_f32_e32 v22, v141, v22
	v_add_f32_e32 v22, v142, v22
	v_add_f32_e32 v22, v143, v22
	v_add_f32_e32 v22, v144, v22
	s_waitcnt lgkmcnt(6)
	v_mfma_f32_16x16x32_bf16 v[10:13], v[26:29], v[2:5], v[10:13]
	s_waitcnt lgkmcnt(4)
	v_mfma_f32_16x16x32_bf16 v[14:17], v[42:45], v[2:5], v[14:17]
	s_waitcnt lgkmcnt(1)
	v_mfma_f32_16x16x32_bf16 v[18:21], v[104:107], v[2:5], v[18:21]
	s_waitcnt lgkmcnt(0)
	v_mfma_f32_16x16x32_bf16 v[6:9], v[108:111], v[2:5], v[6:9]
	v_add_f32_e32 v2, v145, v22
	v_add_f32_e32 v2, v146, v2
	v_add_f32_e32 v2, v147, v2
	v_add_f32_e32 v2, v148, v2
	v_add_f32_e32 v2, v149, v2
	v_add_f32_e32 v2, v150, v2
	v_add_f32_e32 v2, v151, v2
	v_add_f32_e32 v2, v152, v2
	v_add_f32_e32 v2, v153, v2
	v_add_f32_e32 v2, v154, v2
	ds_bpermute_b32 v3, v83, v2
	s_waitcnt lgkmcnt(0)
	v_add_f32_e32 v2, v2, v3
	ds_bpermute_b32 v3, v84, v2
	s_waitcnt lgkmcnt(0)
	v_add_f32_e32 v2, v2, v3
	v_add_f32_e32 v2, v155, v2
	v_div_scale_f32 v3, s[46:47], v2, v2, 1.0
	v_rcp_f32_e32 v22, v3
	v_div_scale_f32 v5, vcc, 1.0, v2, 1.0
	v_fma_f32 v23, -v3, v22, 1.0
	v_fmac_f32_e32 v22, v23, v22
	v_mul_f32_e32 v23, v5, v22
	v_fma_f32 v24, -v3, v23, v5
	v_fmac_f32_e32 v23, v24, v22
	v_fma_f32 v3, -v3, v23, v5
	v_div_fmas_f32 v3, v3, v22, v23
	v_div_fixup_f32 v2, v3, v2, 1.0
	v_mul_f32_e32 v3, v2, v10
	v_mul_f32_e32 v5, v2, v11
	v_mul_f32_e32 v10, v2, v12
	v_mul_f32_e32 v11, v2, v13
	v_mul_f32_e32 v12, v2, v14
	v_mul_f32_e32 v13, v2, v15
	v_mul_f32_e32 v14, v2, v16
	v_mul_f32_e32 v15, v2, v17
	v_mul_f32_e32 v16, v2, v18
	v_mul_f32_e32 v17, v2, v19
	v_mul_f32_e32 v18, v2, v20
	v_mul_f32_e32 v19, v2, v21
	v_mul_f32_e32 v6, v2, v6
	v_mul_f32_e32 v7, v2, v7
	v_mul_f32_e32 v8, v2, v8
	v_mul_f32_e32 v9, v2, v9
	v_cvt_pk_bf16_f32 v2, v3, v5
	v_cvt_pk_bf16_f32 v3, v10, v11
	global_store_dwordx2 v[52:53], v[2:3], off offset:-64
	v_cvt_pk_bf16_f32 v2, v12, v13
	v_cvt_pk_bf16_f32 v3, v14, v15
	global_store_dwordx2 v[52:53], v[2:3], off offset:-32
	v_cvt_pk_bf16_f32 v2, v16, v17
	v_cvt_pk_bf16_f32 v3, v18, v19
	global_store_dwordx2 v[52:53], v[2:3], off
	v_cvt_pk_bf16_f32 v2, v6, v7
	v_cvt_pk_bf16_f32 v3, v8, v9
	global_store_dwordx2 v[52:53], v[2:3], off offset:32
	v_lshl_add_u64 v[52:53], v[52:53], 0, s[36:37]
	s_cbranch_scc1 .LBB0_1420
	s_barrier
	s_branch .LBB0_1401
